# v15 + software-pipelined norm2 phase (3 rows of X in flight per wave, shift/scale prefetched one row ahead, scalar addressing)
# speedup vs baseline: 1.0245x; 1.0118x over previous
; __device__ __forceinline__ int opaque_tid() { int t = threadIdx.x; asm volatile("" : "+v"(t)); return t; }
; __device__ __forceinline__ unsigned pk2(float lo, float hi) { f32x2_t v = {lo, hi}; bf16x2_t b = __builtin_convertvector(v, bf16x2_t); return __builtin_bit_cast(unsigned, b); }
; __device__ __forceinline__ void phase_norm(const Params& P, int l, int which, bool first) {
;     const int tid = opaque_tid(), lane = tid & 63, wave = tid >> 6;
;     const int gw = blockIdx.x * 8 + wave, NGW = gridDim.x * 8;
;     const float* gain = (which == 0 ? P.norm1 : P.norm2) + (size_t)l * DM;
;     const float* mod = (const float*)(P.ws + WS_MOD) + (size_t)l * 17 * MODW + (which == 0 ? 0 : 3 * DM);
;     bf16_t* H = (bf16_t*)(P.ws + WS_H);
;     for (int r = gw; r < ROWS; r += NGW) {
;         const int b = r / TT, t = r - b * TT; const int bb = (t < CTX) ? 16 : b;
;         float* xr = xrow_ptr(P, r);
;         const float* src = first ? ((t < CTX) ? P.ctx + ((size_t)b * CTX + t) * DM : P.x + ((size_t)b * SEQ + (t - CTX)) * DM) : xr;
;         f32x4 v[4]; float s2 = 0.f;
; #pragma unroll
;         for (int j = 0; j < 4; ++j) { v[j] = *((const f32x4*)src + lane + 64 * j); s2 += (v[j].x * v[j].x + v[j].y * v[j].y) + (v[j].z * v[j].z + v[j].w * v[j].w); }
;         if (first) {
; #pragma unroll
;             for (int j = 0; j < 4; ++j) *((f32x4*)xr + lane + 64 * j) = v[j];
;         }
;         const float rstd = 1.0f / sqrtf(wave_sum(s2, lane) * (1.0f / DM) + RMS_EPS);
;         const float* mrow = mod + (size_t)bb * MODW;
; #pragma unroll
;         for (int j = 0; j < 4; ++j) {
;             const int c0 = 4 * (lane + 64 * j);
;             const f32x4 g = *(const f32x4*)(gain + c0), sh = *(const f32x4*)(mrow + c0), scl = *(const f32x4*)(mrow + DM + c0);
;             const f32x4 y = v[j] * rstd * g * (scl + 1.0f) + sh;
;             u32x2 w; w.x = pk2(y.x, y.y); w.y = pk2(y.z, y.w);
;             *(u32x2*)(H + (size_t)r * DM + c0) = w;
;         }
;     }
.LBB0_937:
	s_or_b64 exec, exec, s[10:11]
	s_mov_b64 s[24:25], s[18:19]
	s_waitcnt lgkmcnt(0)
	v_mov_b32_e32 v0, v200
	s_barrier
	v_readlane_b32 s0, v253, 62
	v_ashrrev_i32_e32 v1, 6, v0
	s_nop 0
	v_add_u32_e32 v20, s0, v1
	s_mov_b32 s0, 0x9000
	v_cmp_gt_i32_e32 vcc, s0, v20
	s_and_saveexec_b64 s[10:11], vcc
	s_mov_b32 s7, 0xf800000
	s_mov_b64 s[12:13], 0x1000
	s_cbranch_execz .LBB0_940
	s_load_dwordx4 s[44:47], s[24:25], 0x98
	s_load_dwordx2 s[0:1], s[24:25], 0x78
	v_readlane_b32 s8, v255, 2
	v_readlane_b32 s9, v254, 63
	v_readlane_b32 s100, v255, 0
	v_readfirstlane_b32 s101, v20
	v_and_b32_e32 v120, 63, v200
	v_lshlrev_b32_e32 v121, 3, v120
	v_lshlrev_b32_e32 v32, 2, v120
	v_xor_b32_e32 v122, 4, v32
	v_xor_b32_e32 v123, 8, v32
	v_xor_b32_e32 v124, 16, v32
	v_xor_b32_e32 v125, 32, v32
	v_xor_b32_e32 v126, 64, v32
	v_xor_b32_e32 v127, 0x80, v32
	v_lshlrev_b32_e32 v120, 4, v120
	s_waitcnt lgkmcnt(0)
	s_add_u32 s8, s46, s8
	s_addc_u32 s9, s47, s9
	s_add_u32 s24, s8, 0x104000
	s_addc_u32 s25, s9, 0
	s_lshl_b32 s100, s100, 12
	s_add_u32 s0, s0, s100
	s_addc_u32 s1, s1, 0
	s_add_u32 s36, s46, 0x4500000
	s_addc_u32 s37, s47, 0
	global_load_dwordx4 v[162:165], v120, s[0:1]
	global_load_dwordx4 v[166:169], v120, s[0:1] offset:1024
	global_load_dwordx4 v[170:173], v120, s[0:1] offset:2048
	global_load_dwordx4 v[174:177], v120, s[0:1] offset:3072
	s_lshr_b32 s8, s101, 8
	s_mul_i32 s8, s8, 57
	s_lshr_b32 s8, s8, 9
	s_mul_i32 s9, s8, 0x900
	s_sub_u32 s9, s101, s9
	s_lshl_b32 s0, s8, 11
	s_add_u32 s0, s0, s9
	s_sub_u32 s0, s0, 0x100
	s_lshl_b32 s8, s8, 8
	s_add_u32 s8, s8, s9
	s_cmp_lt_u32 s9, 0x100
	s_cselect_b32 s8, s8, s0
	s_cselect_b32 s0, s36, s44
	s_cselect_b32 s1, s37, s45
	s_lshl_b32 s8, s8, 12
	s_add_u32 s0, s0, s8
	s_addc_u32 s1, s1, 0
	global_load_dwordx4 v[0:3], v120, s[0:1]
	global_load_dwordx4 v[4:7], v120, s[0:1] offset:1024
	global_load_dwordx4 v[8:11], v120, s[0:1] offset:2048
	global_load_dwordx4 v[12:15], v120, s[0:1] offset:3072
	s_add_u32 s100, s101, s68
	s_cmp_le_u32 s100, s71
	s_cselect_b32 s100, s100, s101
	s_lshr_b32 s8, s100, 8
	s_mul_i32 s8, s8, 57
	s_lshr_b32 s8, s8, 9
	s_mul_i32 s9, s8, 0x900
	s_sub_u32 s9, s100, s9
	s_lshl_b32 s0, s8, 11
	s_add_u32 s0, s0, s9
	s_sub_u32 s0, s0, 0x100
	s_lshl_b32 s8, s8, 8
	s_add_u32 s8, s8, s9
	s_cmp_lt_u32 s9, 0x100
	s_cselect_b32 s8, s8, s0
	s_cselect_b32 s0, s36, s44
	s_cselect_b32 s1, s37, s45
	s_lshl_b32 s8, s8, 12
	s_add_u32 s0, s0, s8
	s_addc_u32 s1, s1, 0
	global_load_dwordx4 v[16:19], v120, s[0:1]
	global_load_dwordx4 v[20:23], v120, s[0:1] offset:1024
	global_load_dwordx4 v[24:27], v120, s[0:1] offset:2048
	global_load_dwordx4 v[28:31], v120, s[0:1] offset:3072
	s_mul_i32 s100, s68, 2
	s_add_u32 s100, s100, s101
	s_cmp_le_u32 s100, s71
	s_cselect_b32 s100, s100, s101
	s_lshr_b32 s8, s100, 8
	s_mul_i32 s8, s8, 57
	s_lshr_b32 s8, s8, 9
	s_mul_i32 s9, s8, 0x900
	s_sub_u32 s9, s100, s9
	s_lshl_b32 s0, s8, 11
	s_add_u32 s0, s0, s9
	s_sub_u32 s0, s0, 0x100
	s_lshl_b32 s8, s8, 8
	s_add_u32 s8, s8, s9
	s_cmp_lt_u32 s9, 0x100
	s_cselect_b32 s8, s8, s0
	s_cselect_b32 s0, s36, s44
	s_cselect_b32 s1, s37, s45
	s_lshl_b32 s8, s8, 12
	s_add_u32 s0, s0, s8
	s_addc_u32 s1, s1, 0
	global_load_dwordx4 v[40:43], v120, s[0:1]
	global_load_dwordx4 v[44:47], v120, s[0:1] offset:1024
	global_load_dwordx4 v[48:51], v120, s[0:1] offset:2048
	global_load_dwordx4 v[52:55], v120, s[0:1] offset:3072
	s_lshr_b32 s8, s101, 8
	s_mul_i32 s8, s8, 57
	s_lshr_b32 s8, s8, 9
	s_mul_i32 s9, s8, 0x900
	s_sub_u32 s9, s101, s9
	s_cmp_lt_u32 s9, 0x100
	s_cselect_b32 s8, 16, s8
	s_mul_i32 s8, s8, 0x6000
	s_add_u32 s0, s24, s8
	s_addc_u32 s1, s25, 0
	global_load_dwordx4 v[56:59], v120, s[0:1] offset:-4096
	global_load_dwordx4 v[60:63], v120, s[0:1] offset:-3072
	global_load_dwordx4 v[64:67], v120, s[0:1] offset:-2048
	global_load_dwordx4 v[68:71], v120, s[0:1] offset:-1024
	global_load_dwordx4 v[72:75], v120, s[0:1]
	global_load_dwordx4 v[76:79], v120, s[0:1] offset:1024
	global_load_dwordx4 v[80:83], v120, s[0:1] offset:2048
	global_load_dwordx4 v[84:87], v120, s[0:1] offset:3072
	s_waitcnt vmcnt(16)
	s_add_u32 s100, s101, s68
	s_cmp_le_u32 s100, s71
	s_cselect_b32 s100, s100, s101
	s_lshr_b32 s8, s100, 8
	s_mul_i32 s8, s8, 57
	s_lshr_b32 s8, s8, 9
	s_mul_i32 s9, s8, 0x900
	s_sub_u32 s9, s100, s9
	s_cmp_lt_u32 s9, 0x100
	s_cselect_b32 s8, 16, s8
	s_mul_i32 s8, s8, 0x6000
	s_add_u32 s0, s24, s8
	s_addc_u32 s1, s25, 0
	global_load_dwordx4 v[88:91], v120, s[0:1] offset:-4096
	global_load_dwordx4 v[92:95], v120, s[0:1] offset:-3072
	global_load_dwordx4 v[96:99], v120, s[0:1] offset:-2048
	global_load_dwordx4 v[100:103], v120, s[0:1] offset:-1024
	global_load_dwordx4 v[104:107], v120, s[0:1]
	global_load_dwordx4 v[108:111], v120, s[0:1] offset:1024
	global_load_dwordx4 v[112:115], v120, s[0:1] offset:2048
	global_load_dwordx4 v[116:119], v120, s[0:1] offset:3072
	v_mul_f32_e32 v32, v1, v1
	v_mul_f32_e32 v33, v3, v3
	v_fmac_f32_e32 v32, v0, v0
	v_fmac_f32_e32 v33, v2, v2
	v_add_f32_e32 v34, v32, v33
	v_mul_f32_e32 v32, v5, v5
	v_mul_f32_e32 v33, v7, v7
	v_fmac_f32_e32 v32, v4, v4
	v_fmac_f32_e32 v33, v6, v6
	v_add_f32_e32 v32, v32, v33
	v_add_f32_e32 v34, v34, v32
	v_mul_f32_e32 v32, v9, v9
	v_mul_f32_e32 v33, v11, v11
	v_fmac_f32_e32 v32, v8, v8
	v_fmac_f32_e32 v33, v10, v10
	v_add_f32_e32 v32, v32, v33
	v_add_f32_e32 v34, v34, v32
	v_mul_f32_e32 v32, v13, v13
	v_mul_f32_e32 v33, v15, v15
	v_fmac_f32_e32 v32, v12, v12
	v_fmac_f32_e32 v33, v14, v14
	v_add_f32_e32 v32, v32, v33
	v_add_f32_e32 v34, v34, v32
	ds_bpermute_b32 v32, v122, v34
	s_waitcnt lgkmcnt(0)
	v_add_f32_e32 v34, v34, v32
	ds_bpermute_b32 v32, v123, v34
	s_waitcnt lgkmcnt(0)
; __device__ __forceinline__ unsigned pk2(float lo, float hi) { f32x2_t v = {lo, hi}; bf16x2_t b = __builtin_convertvector(v, bf16x2_t); return __builtin_bit_cast(unsigned, b); }
; __device__ __forceinline__ void phase_norm(const Params& P, int l, int which, bool first) {
;     ...
;         f32x4 v[4]; float s2 = 0.f;
; #pragma unroll
;         for (int j = 0; j < 4; ++j) { v[j] = *((const f32x4*)src + lane + 64 * j); s2 += (v[j].x * v[j].x + v[j].y * v[j].y) + (v[j].z * v[j].z + v[j].w * v[j].w); }
;         if (first) {
; #pragma unroll
;             for (int j = 0; j < 4; ++j) *((f32x4*)xr + lane + 64 * j) = v[j];
;         }
;         const float rstd = 1.0f / sqrtf(wave_sum(s2, lane) * (1.0f / DM) + RMS_EPS);
;         const float* mrow = mod + (size_t)bb * MODW;
; #pragma unroll
;         for (int j = 0; j < 4; ++j) {
;             const int c0 = 4 * (lane + 64 * j);
;             const f32x4 g = *(const f32x4*)(gain + c0), sh = *(const f32x4*)(mrow + c0), scl = *(const f32x4*)(mrow + DM + c0);
;             const f32x4 y = v[j] * rstd * g * (scl + 1.0f) + sh;
;             u32x2 w; w.x = pk2(y.x, y.y); w.y = pk2(y.z, y.w);
;             *(u32x2*)(H + (size_t)r * DM + c0) = w;
;         }
	v_add_f32_e32 v34, v34, v32
	ds_bpermute_b32 v32, v124, v34
	s_waitcnt lgkmcnt(0)
	v_add_f32_e32 v34, v34, v32
	ds_bpermute_b32 v32, v125, v34
	s_waitcnt lgkmcnt(0)
	v_add_f32_e32 v34, v34, v32
	ds_bpermute_b32 v32, v126, v34
	s_waitcnt lgkmcnt(0)
	v_add_f32_e32 v34, v34, v32
	ds_bpermute_b32 v32, v127, v34
	s_waitcnt lgkmcnt(0)
	v_add_f32_e32 v34, v34, v32
	v_fmamk_f32 v34, v34, 0x3a800000, v201
	v_cmp_gt_f32_e32 vcc, 0xf800000, v34
	v_mul_f32_e32 v32, 0x4f800000, v34
	s_nop 0
	v_cndmask_b32_e32 v34, v34, v32, vcc
	v_sqrt_f32_e32 v32, v34
	s_nop 0
	v_add_u32_e32 v35, -1, v32
	v_fma_f32 v36, -v35, v32, v34
	v_cmp_ge_f32_e64 s[42:43], 0, v36
	v_add_u32_e32 v36, 1, v32
	s_nop 0
	v_cndmask_b32_e64 v35, v32, v35, s[42:43]
	v_fma_f32 v32, -v36, v32, v34
	v_cmp_lt_f32_e64 s[42:43], 0, v32
	s_nop 1
	v_cndmask_b32_e64 v32, v35, v36, s[42:43]
	v_mul_f32_e32 v35, 0x37800000, v32
	v_cndmask_b32_e32 v32, v32, v35, vcc
	v_cmp_class_f32_e32 vcc, v34, v202
	s_nop 1
	v_cndmask_b32_e32 v34, v32, v34, vcc
	v_div_scale_f32 v32, s[42:43], v34, v34, 1.0
	v_rcp_f32_e32 v35, v32
	s_nop 0
	v_fma_f32 v36, -v32, v35, 1.0
	v_fmac_f32_e32 v35, v36, v35
	v_div_scale_f32 v36, vcc, 1.0, v34, 1.0
	v_mul_f32_e32 v37, v36, v35
	v_fma_f32 v178, -v32, v37, v36
	v_fmac_f32_e32 v37, v178, v35
	v_fma_f32 v32, -v32, v37, v36
	v_div_fmas_f32 v32, v32, v35, v37
	v_div_fixup_f32 v179, v32, v34, 1.0
	s_lshl_b32 s8, s101, 11
	s_add_u32 s0, s46, s8
	s_addc_u32 s1, s47, 0
	s_add_u32 s0, s0, 0x5500000
	s_addc_u32 s1, s1, 0
	s_waitcnt vmcnt(8)
	v_mul_f32_e32 v193, v0, v179
	v_add_f32_e32 v192, 1.0, v72
	v_mul_f32_e32 v193, v162, v193
	v_fma_f32 v180, v192, v193, v56
	v_mul_f32_e32 v193, v1, v179
	v_add_f32_e32 v192, 1.0, v73
	v_mul_f32_e32 v193, v163, v193
	v_fma_f32 v181, v192, v193, v57
	v_mul_f32_e32 v193, v2, v179
	v_add_f32_e32 v192, 1.0, v74
	v_mul_f32_e32 v193, v164, v193
	v_fma_f32 v182, v192, v193, v58
	v_mul_f32_e32 v193, v3, v179
	v_add_f32_e32 v192, 1.0, v75
	v_mul_f32_e32 v193, v165, v193
	v_fma_f32 v183, v192, v193, v59
	v_cvt_pk_bf16_f32 v184, v180, v181
	v_cvt_pk_bf16_f32 v185, v182, v183
	global_store_dwordx2 v121, v[184:185], s[0:1]
	v_mul_f32_e32 v193, v4, v179
	v_add_f32_e32 v192, 1.0, v76
	v_mul_f32_e32 v193, v166, v193
	v_fma_f32 v180, v192, v193, v60
	v_mul_f32_e32 v193, v5, v179
	v_add_f32_e32 v192, 1.0, v77
	v_mul_f32_e32 v193, v167, v193
	v_fma_f32 v181, v192, v193, v61
	v_mul_f32_e32 v193, v6, v179
	v_add_f32_e32 v192, 1.0, v78
	v_mul_f32_e32 v193, v168, v193
	v_fma_f32 v182, v192, v193, v62
	v_mul_f32_e32 v193, v7, v179
	v_add_f32_e32 v192, 1.0, v79
	v_mul_f32_e32 v193, v169, v193
	v_fma_f32 v183, v192, v193, v63
	v_cvt_pk_bf16_f32 v186, v180, v181
	v_cvt_pk_bf16_f32 v187, v182, v183
	global_store_dwordx2 v121, v[186:187], s[0:1] offset:512
	v_mul_f32_e32 v193, v8, v179
	v_add_f32_e32 v192, 1.0, v80
	v_mul_f32_e32 v193, v170, v193
	v_fma_f32 v180, v192, v193, v64
	v_mul_f32_e32 v193, v9, v179
	v_add_f32_e32 v192, 1.0, v81
	v_mul_f32_e32 v193, v171, v193
	v_fma_f32 v181, v192, v193, v65
	v_mul_f32_e32 v193, v10, v179
	v_add_f32_e32 v192, 1.0, v82
	v_mul_f32_e32 v193, v172, v193
	v_fma_f32 v182, v192, v193, v66
	v_mul_f32_e32 v193, v11, v179
	v_add_f32_e32 v192, 1.0, v83
	v_mul_f32_e32 v193, v173, v193
	v_fma_f32 v183, v192, v193, v67
	v_cvt_pk_bf16_f32 v188, v180, v181
	v_cvt_pk_bf16_f32 v189, v182, v183
	global_store_dwordx2 v121, v[188:189], s[0:1] offset:1024
	v_mul_f32_e32 v193, v12, v179
	v_add_f32_e32 v192, 1.0, v84
	v_mul_f32_e32 v193, v174, v193
	v_fma_f32 v180, v192, v193, v68
	v_mul_f32_e32 v193, v13, v179
	v_add_f32_e32 v192, 1.0, v85
	v_mul_f32_e32 v193, v175, v193
	v_fma_f32 v181, v192, v193, v69
	v_mul_f32_e32 v193, v14, v179
	v_add_f32_e32 v192, 1.0, v86
	v_mul_f32_e32 v193, v176, v193
	v_fma_f32 v182, v192, v193, v70
	v_mul_f32_e32 v193, v15, v179
	v_add_f32_e32 v192, 1.0, v87
	v_mul_f32_e32 v193, v177, v193
	v_fma_f32 v183, v192, v193, v71
	v_cvt_pk_bf16_f32 v190, v180, v181
	v_cvt_pk_bf16_f32 v191, v182, v183
	global_store_dwordx2 v121, v[190:191], s[0:1] offset:1536
	s_mul_i32 s100, s68, 3
	s_add_u32 s100, s100, s101
	s_cmp_le_u32 s100, s71
	s_cselect_b32 s100, s100, s101
	s_lshr_b32 s8, s100, 8
	s_mul_i32 s8, s8, 57
	s_lshr_b32 s8, s8, 9
	s_mul_i32 s9, s8, 0x900
	s_sub_u32 s9, s100, s9
	s_lshl_b32 s0, s8, 11
	s_add_u32 s0, s0, s9
	s_sub_u32 s0, s0, 0x100
	s_lshl_b32 s8, s8, 8
	s_add_u32 s8, s8, s9
	s_cmp_lt_u32 s9, 0x100
	s_cselect_b32 s8, s8, s0
	s_cselect_b32 s0, s36, s44
	s_cselect_b32 s1, s37, s45
	s_lshl_b32 s8, s8, 12
	s_add_u32 s0, s0, s8
	s_addc_u32 s1, s1, 0
	global_load_dwordx4 v[0:3], v120, s[0:1]
	global_load_dwordx4 v[4:7], v120, s[0:1] offset:1024
	global_load_dwordx4 v[8:11], v120, s[0:1] offset:2048
	global_load_dwordx4 v[12:15], v120, s[0:1] offset:3072
	s_add_u32 s101, s101, s68
	s_cmp_gt_u32 s101, s71
	s_cbranch_scc1 .Lnf_n2_exit
; __device__ __forceinline__ unsigned pk2(float lo, float hi) { f32x2_t v = {lo, hi}; bf16x2_t b = __builtin_convertvector(v, bf16x2_t); return __builtin_bit_cast(unsigned, b); }
; __device__ __forceinline__ void phase_norm(const Params& P, int l, int which, bool first) {
;     ...
;     for (int r = gw; r < ROWS; r += NGW) {
;         const int b = r / TT, t = r - b * TT; const int bb = (t < CTX) ? 16 : b;
;         float* xr = xrow_ptr(P, r);
;         const float* src = first ? ((t < CTX) ? P.ctx + ((size_t)b * CTX + t) * DM : P.x + ((size_t)b * SEQ + (t - CTX)) * DM) : xr;
;         f32x4 v[4]; float s2 = 0.f;
; #pragma unroll
;         for (int j = 0; j < 4; ++j) { v[j] = *((const f32x4*)src + lane + 64 * j); s2 += (v[j].x * v[j].x + v[j].y * v[j].y) + (v[j].z * v[j].z + v[j].w * v[j].w); }
;         if (first) {
; #pragma unroll
;             for (int j = 0; j < 4; ++j) *((f32x4*)xr + lane + 64 * j) = v[j];
;         }
;         const float rstd = 1.0f / sqrtf(wave_sum(s2, lane) * (1.0f / DM) + RMS_EPS);
;         const float* mrow = mod + (size_t)bb * MODW;
; #pragma unroll
;         for (int j = 0; j < 4; ++j) {
;             const int c0 = 4 * (lane + 64 * j);
;             const f32x4 g = *(const f32x4*)(gain + c0), sh = *(const f32x4*)(mrow + c0), scl = *(const f32x4*)(mrow + DM + c0);
;             const f32x4 y = v[j] * rstd * g * (scl + 1.0f) + sh;
;             u32x2 w; w.x = pk2(y.x, y.y); w.y = pk2(y.z, y.w);
;             *(u32x2*)(H + (size_t)r * DM + c0) = w;
;         }
	s_waitcnt vmcnt(28)
	s_add_u32 s100, s101, s68
	s_cmp_le_u32 s100, s71
	s_cselect_b32 s100, s100, s101
	s_lshr_b32 s8, s100, 8
	s_mul_i32 s8, s8, 57
	s_lshr_b32 s8, s8, 9
	s_mul_i32 s9, s8, 0x900
	s_sub_u32 s9, s100, s9
	s_cmp_lt_u32 s9, 0x100
	s_cselect_b32 s8, 16, s8
	s_mul_i32 s8, s8, 0x6000
	s_add_u32 s0, s24, s8
	s_addc_u32 s1, s25, 0
	global_load_dwordx4 v[130:133], v120, s[0:1] offset:-4096
	global_load_dwordx4 v[134:137], v120, s[0:1] offset:-3072
	global_load_dwordx4 v[138:141], v120, s[0:1] offset:-2048
	global_load_dwordx4 v[142:145], v120, s[0:1] offset:-1024
	global_load_dwordx4 v[146:149], v120, s[0:1]
	global_load_dwordx4 v[150:153], v120, s[0:1] offset:1024
	global_load_dwordx4 v[154:157], v120, s[0:1] offset:2048
	global_load_dwordx4 v[158:161], v120, s[0:1] offset:3072
	v_mul_f32_e32 v32, v17, v17
	v_mul_f32_e32 v33, v19, v19
	v_fmac_f32_e32 v32, v16, v16
	v_fmac_f32_e32 v33, v18, v18
	v_add_f32_e32 v34, v32, v33
	v_mul_f32_e32 v32, v21, v21
	v_mul_f32_e32 v33, v23, v23
	v_fmac_f32_e32 v32, v20, v20
	v_fmac_f32_e32 v33, v22, v22
	v_add_f32_e32 v32, v32, v33
	v_add_f32_e32 v34, v34, v32
	v_mul_f32_e32 v32, v25, v25
	v_mul_f32_e32 v33, v27, v27
	v_fmac_f32_e32 v32, v24, v24
	v_fmac_f32_e32 v33, v26, v26
	v_add_f32_e32 v32, v32, v33
	v_add_f32_e32 v34, v34, v32
	v_mul_f32_e32 v32, v29, v29
	v_mul_f32_e32 v33, v31, v31
	v_fmac_f32_e32 v32, v28, v28
	v_fmac_f32_e32 v33, v30, v30
	v_add_f32_e32 v32, v32, v33
	v_add_f32_e32 v34, v34, v32
	ds_bpermute_b32 v32, v122, v34
	s_waitcnt lgkmcnt(0)
	v_add_f32_e32 v34, v34, v32
	ds_bpermute_b32 v32, v123, v34
	s_waitcnt lgkmcnt(0)
	v_add_f32_e32 v34, v34, v32
	ds_bpermute_b32 v32, v124, v34
	s_waitcnt lgkmcnt(0)
	v_add_f32_e32 v34, v34, v32
	ds_bpermute_b32 v32, v125, v34
	s_waitcnt lgkmcnt(0)
	v_add_f32_e32 v34, v34, v32
	ds_bpermute_b32 v32, v126, v34
	s_waitcnt lgkmcnt(0)
	v_add_f32_e32 v34, v34, v32
	ds_bpermute_b32 v32, v127, v34
	s_waitcnt lgkmcnt(0)
	v_add_f32_e32 v34, v34, v32
	v_fmamk_f32 v34, v34, 0x3a800000, v201
	v_cmp_gt_f32_e32 vcc, 0xf800000, v34
	v_mul_f32_e32 v32, 0x4f800000, v34
	s_nop 0
	v_cndmask_b32_e32 v34, v34, v32, vcc
	v_sqrt_f32_e32 v32, v34
	s_nop 0
	v_add_u32_e32 v35, -1, v32
	v_fma_f32 v36, -v35, v32, v34
	v_cmp_ge_f32_e64 s[42:43], 0, v36
	v_add_u32_e32 v36, 1, v32
	s_nop 0
	v_cndmask_b32_e64 v35, v32, v35, s[42:43]
	v_fma_f32 v32, -v36, v32, v34
	v_cmp_lt_f32_e64 s[42:43], 0, v32
	s_nop 1
	v_cndmask_b32_e64 v32, v35, v36, s[42:43]
	v_mul_f32_e32 v35, 0x37800000, v32
	v_cndmask_b32_e32 v32, v32, v35, vcc
	v_cmp_class_f32_e32 vcc, v34, v202
	s_nop 1
	v_cndmask_b32_e32 v34, v32, v34, vcc
	v_div_scale_f32 v32, s[42:43], v34, v34, 1.0
	v_rcp_f32_e32 v35, v32
	s_nop 0
	v_fma_f32 v36, -v32, v35, 1.0
	v_fmac_f32_e32 v35, v36, v35
	v_div_scale_f32 v36, vcc, 1.0, v34, 1.0
	v_mul_f32_e32 v37, v36, v35
	v_fma_f32 v178, -v32, v37, v36
	v_fmac_f32_e32 v37, v178, v35
	v_fma_f32 v32, -v32, v37, v36
	v_div_fmas_f32 v32, v32, v35, v37
	v_div_fixup_f32 v179, v32, v34, 1.0
	s_lshl_b32 s8, s101, 11
	s_add_u32 s0, s46, s8
	s_addc_u32 s1, s47, 0
	s_add_u32 s0, s0, 0x5500000
	s_addc_u32 s1, s1, 0
	s_waitcnt vmcnt(16)
	v_mul_f32_e32 v193, v16, v179
	v_add_f32_e32 v192, 1.0, v104
	v_mul_f32_e32 v193, v162, v193
	v_fma_f32 v180, v192, v193, v88
	v_mul_f32_e32 v193, v17, v179
	v_add_f32_e32 v192, 1.0, v105
	v_mul_f32_e32 v193, v163, v193
	v_fma_f32 v181, v192, v193, v89
	v_mul_f32_e32 v193, v18, v179
	v_add_f32_e32 v192, 1.0, v106
	v_mul_f32_e32 v193, v164, v193
	v_fma_f32 v182, v192, v193, v90
	v_mul_f32_e32 v193, v19, v179
	v_add_f32_e32 v192, 1.0, v107
	v_mul_f32_e32 v193, v165, v193
	v_fma_f32 v183, v192, v193, v91
	v_cvt_pk_bf16_f32 v184, v180, v181
	v_cvt_pk_bf16_f32 v185, v182, v183
	global_store_dwordx2 v121, v[184:185], s[0:1]
	v_mul_f32_e32 v193, v20, v179
	v_add_f32_e32 v192, 1.0, v108
	v_mul_f32_e32 v193, v166, v193
	v_fma_f32 v180, v192, v193, v92
	v_mul_f32_e32 v193, v21, v179
	v_add_f32_e32 v192, 1.0, v109
	v_mul_f32_e32 v193, v167, v193
	v_fma_f32 v181, v192, v193, v93
	v_mul_f32_e32 v193, v22, v179
	v_add_f32_e32 v192, 1.0, v110
	v_mul_f32_e32 v193, v168, v193
	v_fma_f32 v182, v192, v193, v94
	v_mul_f32_e32 v193, v23, v179
	v_add_f32_e32 v192, 1.0, v111
	v_mul_f32_e32 v193, v169, v193
	v_fma_f32 v183, v192, v193, v95
	v_cvt_pk_bf16_f32 v186, v180, v181
	v_cvt_pk_bf16_f32 v187, v182, v183
	global_store_dwordx2 v121, v[186:187], s[0:1] offset:512
	v_mul_f32_e32 v193, v24, v179
	v_add_f32_e32 v192, 1.0, v112
	v_mul_f32_e32 v193, v170, v193
	v_fma_f32 v180, v192, v193, v96
	v_mul_f32_e32 v193, v25, v179
	v_add_f32_e32 v192, 1.0, v113
	v_mul_f32_e32 v193, v171, v193
	v_fma_f32 v181, v192, v193, v97
	v_mul_f32_e32 v193, v26, v179
	v_add_f32_e32 v192, 1.0, v114
	v_mul_f32_e32 v193, v172, v193
	v_fma_f32 v182, v192, v193, v98
	v_mul_f32_e32 v193, v27, v179
	v_add_f32_e32 v192, 1.0, v115
	v_mul_f32_e32 v193, v173, v193
	v_fma_f32 v183, v192, v193, v99
	v_cvt_pk_bf16_f32 v188, v180, v181
	v_cvt_pk_bf16_f32 v189, v182, v183
	global_store_dwordx2 v121, v[188:189], s[0:1] offset:1024
	v_mul_f32_e32 v193, v28, v179
	v_add_f32_e32 v192, 1.0, v116
	v_mul_f32_e32 v193, v174, v193
	v_fma_f32 v180, v192, v193, v100
	v_mul_f32_e32 v193, v29, v179
	v_add_f32_e32 v192, 1.0, v117
	v_mul_f32_e32 v193, v175, v193
	v_fma_f32 v181, v192, v193, v101
	v_mul_f32_e32 v193, v30, v179
	v_add_f32_e32 v192, 1.0, v118
	v_mul_f32_e32 v193, v176, v193
	v_fma_f32 v182, v192, v193, v102
	v_mul_f32_e32 v193, v31, v179
	v_add_f32_e32 v192, 1.0, v119
	v_mul_f32_e32 v193, v177, v193
	v_fma_f32 v183, v192, v193, v103
	v_cvt_pk_bf16_f32 v190, v180, v181
	v_cvt_pk_bf16_f32 v191, v182, v183
	global_store_dwordx2 v121, v[190:191], s[0:1] offset:1536
	s_mul_i32 s100, s68, 3
	s_add_u32 s100, s100, s101
	s_cmp_le_u32 s100, s71
	s_cselect_b32 s100, s100, s101
	s_lshr_b32 s8, s100, 8
	s_mul_i32 s8, s8, 57
	s_lshr_b32 s8, s8, 9
	s_mul_i32 s9, s8, 0x900
	s_sub_u32 s9, s100, s9
	s_lshl_b32 s0, s8, 11
	s_add_u32 s0, s0, s9
	s_sub_u32 s0, s0, 0x100
	s_lshl_b32 s8, s8, 8
	s_add_u32 s8, s8, s9
	s_cmp_lt_u32 s9, 0x100
	s_cselect_b32 s8, s8, s0
	s_cselect_b32 s0, s36, s44
	s_cselect_b32 s1, s37, s45
	s_lshl_b32 s8, s8, 12
	s_add_u32 s0, s0, s8
	s_addc_u32 s1, s1, 0
	global_load_dwordx4 v[16:19], v120, s[0:1]
	global_load_dwordx4 v[20:23], v120, s[0:1] offset:1024
	global_load_dwordx4 v[24:27], v120, s[0:1] offset:2048
	global_load_dwordx4 v[28:31], v120, s[0:1] offset:3072
	s_add_u32 s101, s101, s68
	s_cmp_gt_u32 s101, s71
	s_cbranch_scc1 .Lnf_n2_exit
; __device__ __forceinline__ unsigned pk2(float lo, float hi) { f32x2_t v = {lo, hi}; bf16x2_t b = __builtin_convertvector(v, bf16x2_t); return __builtin_bit_cast(unsigned, b); }
; __device__ __forceinline__ void phase_norm(const Params& P, int l, int which, bool first) {
;     ...
;     for (int r = gw; r < ROWS; r += NGW) {
;         const int b = r / TT, t = r - b * TT; const int bb = (t < CTX) ? 16 : b;
;         float* xr = xrow_ptr(P, r);
;         const float* src = first ? ((t < CTX) ? P.ctx + ((size_t)b * CTX + t) * DM : P.x + ((size_t)b * SEQ + (t - CTX)) * DM) : xr;
;         f32x4 v[4]; float s2 = 0.f;
; #pragma unroll
;         for (int j = 0; j < 4; ++j) { v[j] = *((const f32x4*)src + lane + 64 * j); s2 += (v[j].x * v[j].x + v[j].y * v[j].y) + (v[j].z * v[j].z + v[j].w * v[j].w); }
;         if (first) {
; #pragma unroll
;             for (int j = 0; j < 4; ++j) *((f32x4*)xr + lane + 64 * j) = v[j];
;         }
;         const float rstd = 1.0f / sqrtf(wave_sum(s2, lane) * (1.0f / DM) + RMS_EPS);
;         const float* mrow = mod + (size_t)bb * MODW;
; #pragma unroll
;         for (int j = 0; j < 4; ++j) {
;             const int c0 = 4 * (lane + 64 * j);
;             const f32x4 g = *(const f32x4*)(gain + c0), sh = *(const f32x4*)(mrow + c0), scl = *(const f32x4*)(mrow + DM + c0);
;             const f32x4 y = v[j] * rstd * g * (scl + 1.0f) + sh;
;             u32x2 w; w.x = pk2(y.x, y.y); w.y = pk2(y.z, y.w);
;             *(u32x2*)(H + (size_t)r * DM + c0) = w;
;         }
	s_waitcnt vmcnt(32)
	s_add_u32 s100, s101, s68
	s_cmp_le_u32 s100, s71
	s_cselect_b32 s100, s100, s101
	s_lshr_b32 s8, s100, 8
	s_mul_i32 s8, s8, 57
	s_lshr_b32 s8, s8, 9
	s_mul_i32 s9, s8, 0x900
	s_sub_u32 s9, s100, s9
	s_cmp_lt_u32 s9, 0x100
	s_cselect_b32 s8, 16, s8
	s_mul_i32 s8, s8, 0x6000
	s_add_u32 s0, s24, s8
	s_addc_u32 s1, s25, 0
	global_load_dwordx4 v[56:59], v120, s[0:1] offset:-4096
	global_load_dwordx4 v[60:63], v120, s[0:1] offset:-3072
	global_load_dwordx4 v[64:67], v120, s[0:1] offset:-2048
	global_load_dwordx4 v[68:71], v120, s[0:1] offset:-1024
	global_load_dwordx4 v[72:75], v120, s[0:1]
	global_load_dwordx4 v[76:79], v120, s[0:1] offset:1024
	global_load_dwordx4 v[80:83], v120, s[0:1] offset:2048
	global_load_dwordx4 v[84:87], v120, s[0:1] offset:3072
	v_mul_f32_e32 v32, v41, v41
	v_mul_f32_e32 v33, v43, v43
	v_fmac_f32_e32 v32, v40, v40
	v_fmac_f32_e32 v33, v42, v42
	v_add_f32_e32 v34, v32, v33
	v_mul_f32_e32 v32, v45, v45
	v_mul_f32_e32 v33, v47, v47
	v_fmac_f32_e32 v32, v44, v44
	v_fmac_f32_e32 v33, v46, v46
	v_add_f32_e32 v32, v32, v33
	v_add_f32_e32 v34, v34, v32
	v_mul_f32_e32 v32, v49, v49
	v_mul_f32_e32 v33, v51, v51
	v_fmac_f32_e32 v32, v48, v48
	v_fmac_f32_e32 v33, v50, v50
	v_add_f32_e32 v32, v32, v33
	v_add_f32_e32 v34, v34, v32
	v_mul_f32_e32 v32, v53, v53
	v_mul_f32_e32 v33, v55, v55
	v_fmac_f32_e32 v32, v52, v52
	v_fmac_f32_e32 v33, v54, v54
	v_add_f32_e32 v32, v32, v33
	v_add_f32_e32 v34, v34, v32
	ds_bpermute_b32 v32, v122, v34
	s_waitcnt lgkmcnt(0)
	v_add_f32_e32 v34, v34, v32
	ds_bpermute_b32 v32, v123, v34
	s_waitcnt lgkmcnt(0)
	v_add_f32_e32 v34, v34, v32
	ds_bpermute_b32 v32, v124, v34
	s_waitcnt lgkmcnt(0)
	v_add_f32_e32 v34, v34, v32
	ds_bpermute_b32 v32, v125, v34
	s_waitcnt lgkmcnt(0)
	v_add_f32_e32 v34, v34, v32
	ds_bpermute_b32 v32, v126, v34
	s_waitcnt lgkmcnt(0)
	v_add_f32_e32 v34, v34, v32
	ds_bpermute_b32 v32, v127, v34
	s_waitcnt lgkmcnt(0)
	v_add_f32_e32 v34, v34, v32
	v_fmamk_f32 v34, v34, 0x3a800000, v201
	v_cmp_gt_f32_e32 vcc, 0xf800000, v34
	v_mul_f32_e32 v32, 0x4f800000, v34
	s_nop 0
	v_cndmask_b32_e32 v34, v34, v32, vcc
	v_sqrt_f32_e32 v32, v34
	s_nop 0
	v_add_u32_e32 v35, -1, v32
	v_fma_f32 v36, -v35, v32, v34
	v_cmp_ge_f32_e64 s[42:43], 0, v36
	v_add_u32_e32 v36, 1, v32
	s_nop 0
	v_cndmask_b32_e64 v35, v32, v35, s[42:43]
	v_fma_f32 v32, -v36, v32, v34
	v_cmp_lt_f32_e64 s[42:43], 0, v32
	s_nop 1
	v_cndmask_b32_e64 v32, v35, v36, s[42:43]
	v_mul_f32_e32 v35, 0x37800000, v32
	v_cndmask_b32_e32 v32, v32, v35, vcc
	v_cmp_class_f32_e32 vcc, v34, v202
	s_nop 1
	v_cndmask_b32_e32 v34, v32, v34, vcc
	v_div_scale_f32 v32, s[42:43], v34, v34, 1.0
	v_rcp_f32_e32 v35, v32
	s_nop 0
	v_fma_f32 v36, -v32, v35, 1.0
	v_fmac_f32_e32 v35, v36, v35
	v_div_scale_f32 v36, vcc, 1.0, v34, 1.0
	v_mul_f32_e32 v37, v36, v35
	v_fma_f32 v178, -v32, v37, v36
	v_fmac_f32_e32 v37, v178, v35
	v_fma_f32 v32, -v32, v37, v36
	v_div_fmas_f32 v32, v32, v35, v37
	v_div_fixup_f32 v179, v32, v34, 1.0
	s_lshl_b32 s8, s101, 11
	s_add_u32 s0, s46, s8
	s_addc_u32 s1, s47, 0
	s_add_u32 s0, s0, 0x5500000
	s_addc_u32 s1, s1, 0
	s_waitcnt vmcnt(16)
	v_mul_f32_e32 v193, v40, v179
	v_add_f32_e32 v192, 1.0, v146
	v_mul_f32_e32 v193, v162, v193
	v_fma_f32 v180, v192, v193, v130
	v_mul_f32_e32 v193, v41, v179
	v_add_f32_e32 v192, 1.0, v147
	v_mul_f32_e32 v193, v163, v193
	v_fma_f32 v181, v192, v193, v131
	v_mul_f32_e32 v193, v42, v179
	v_add_f32_e32 v192, 1.0, v148
	v_mul_f32_e32 v193, v164, v193
	v_fma_f32 v182, v192, v193, v132
	v_mul_f32_e32 v193, v43, v179
	v_add_f32_e32 v192, 1.0, v149
	v_mul_f32_e32 v193, v165, v193
	v_fma_f32 v183, v192, v193, v133
	v_cvt_pk_bf16_f32 v184, v180, v181
	v_cvt_pk_bf16_f32 v185, v182, v183
	global_store_dwordx2 v121, v[184:185], s[0:1]
	v_mul_f32_e32 v193, v44, v179
	v_add_f32_e32 v192, 1.0, v150
	v_mul_f32_e32 v193, v166, v193
	v_fma_f32 v180, v192, v193, v134
	v_mul_f32_e32 v193, v45, v179
	v_add_f32_e32 v192, 1.0, v151
	v_mul_f32_e32 v193, v167, v193
	v_fma_f32 v181, v192, v193, v135
	v_mul_f32_e32 v193, v46, v179
	v_add_f32_e32 v192, 1.0, v152
	v_mul_f32_e32 v193, v168, v193
	v_fma_f32 v182, v192, v193, v136
	v_mul_f32_e32 v193, v47, v179
	v_add_f32_e32 v192, 1.0, v153
	v_mul_f32_e32 v193, v169, v193
	v_fma_f32 v183, v192, v193, v137
	v_cvt_pk_bf16_f32 v186, v180, v181
	v_cvt_pk_bf16_f32 v187, v182, v183
	global_store_dwordx2 v121, v[186:187], s[0:1] offset:512
	v_mul_f32_e32 v193, v48, v179
	v_add_f32_e32 v192, 1.0, v154
	v_mul_f32_e32 v193, v170, v193
	v_fma_f32 v180, v192, v193, v138
	v_mul_f32_e32 v193, v49, v179
	v_add_f32_e32 v192, 1.0, v155
	v_mul_f32_e32 v193, v171, v193
	v_fma_f32 v181, v192, v193, v139
	v_mul_f32_e32 v193, v50, v179
	v_add_f32_e32 v192, 1.0, v156
	v_mul_f32_e32 v193, v172, v193
	v_fma_f32 v182, v192, v193, v140
	v_mul_f32_e32 v193, v51, v179
	v_add_f32_e32 v192, 1.0, v157
	v_mul_f32_e32 v193, v173, v193
	v_fma_f32 v183, v192, v193, v141
	v_cvt_pk_bf16_f32 v188, v180, v181
	v_cvt_pk_bf16_f32 v189, v182, v183
	global_store_dwordx2 v121, v[188:189], s[0:1] offset:1024
	v_mul_f32_e32 v193, v52, v179
	v_add_f32_e32 v192, 1.0, v158
	v_mul_f32_e32 v193, v174, v193
	v_fma_f32 v180, v192, v193, v142
	v_mul_f32_e32 v193, v53, v179
	v_add_f32_e32 v192, 1.0, v159
	v_mul_f32_e32 v193, v175, v193
	v_fma_f32 v181, v192, v193, v143
	v_mul_f32_e32 v193, v54, v179
	v_add_f32_e32 v192, 1.0, v160
	v_mul_f32_e32 v193, v176, v193
	v_fma_f32 v182, v192, v193, v144
	v_mul_f32_e32 v193, v55, v179
	v_add_f32_e32 v192, 1.0, v161
	v_mul_f32_e32 v193, v177, v193
	v_fma_f32 v183, v192, v193, v145
	v_cvt_pk_bf16_f32 v190, v180, v181
	v_cvt_pk_bf16_f32 v191, v182, v183
	global_store_dwordx2 v121, v[190:191], s[0:1] offset:1536
	s_mul_i32 s100, s68, 3
	s_add_u32 s100, s100, s101
	s_cmp_le_u32 s100, s71
	s_cselect_b32 s100, s100, s101
	s_lshr_b32 s8, s100, 8
	s_mul_i32 s8, s8, 57
	s_lshr_b32 s8, s8, 9
	s_mul_i32 s9, s8, 0x900
	s_sub_u32 s9, s100, s9
	s_lshl_b32 s0, s8, 11
	s_add_u32 s0, s0, s9
	s_sub_u32 s0, s0, 0x100
	s_lshl_b32 s8, s8, 8
	s_add_u32 s8, s8, s9
	s_cmp_lt_u32 s9, 0x100
	s_cselect_b32 s8, s8, s0
	s_cselect_b32 s0, s36, s44
	s_cselect_b32 s1, s37, s45
	s_lshl_b32 s8, s8, 12
	s_add_u32 s0, s0, s8
	s_addc_u32 s1, s1, 0
	global_load_dwordx4 v[40:43], v120, s[0:1]
	global_load_dwordx4 v[44:47], v120, s[0:1] offset:1024
	global_load_dwordx4 v[48:51], v120, s[0:1] offset:2048
	global_load_dwordx4 v[52:55], v120, s[0:1] offset:3072
	s_add_u32 s101, s101, s68
	s_cmp_gt_u32 s101, s71
	s_cbranch_scc1 .Lnf_n2_exit
; __device__ __forceinline__ unsigned pk2(float lo, float hi) { f32x2_t v = {lo, hi}; bf16x2_t b = __builtin_convertvector(v, bf16x2_t); return __builtin_bit_cast(unsigned, b); }
; __device__ __forceinline__ void phase_norm(const Params& P, int l, int which, bool first) {
;     ...
;     for (int r = gw; r < ROWS; r += NGW) {
;         const int b = r / TT, t = r - b * TT; const int bb = (t < CTX) ? 16 : b;
;         float* xr = xrow_ptr(P, r);
;         const float* src = first ? ((t < CTX) ? P.ctx + ((size_t)b * CTX + t) * DM : P.x + ((size_t)b * SEQ + (t - CTX)) * DM) : xr;
;         f32x4 v[4]; float s2 = 0.f;
; #pragma unroll
;         for (int j = 0; j < 4; ++j) { v[j] = *((const f32x4*)src + lane + 64 * j); s2 += (v[j].x * v[j].x + v[j].y * v[j].y) + (v[j].z * v[j].z + v[j].w * v[j].w); }
;         if (first) {
; #pragma unroll
;             for (int j = 0; j < 4; ++j) *((f32x4*)xr + lane + 64 * j) = v[j];
;         }
;         const float rstd = 1.0f / sqrtf(wave_sum(s2, lane) * (1.0f / DM) + RMS_EPS);
;         const float* mrow = mod + (size_t)bb * MODW;
; #pragma unroll
;         for (int j = 0; j < 4; ++j) {
;             const int c0 = 4 * (lane + 64 * j);
;             const f32x4 g = *(const f32x4*)(gain + c0), sh = *(const f32x4*)(mrow + c0), scl = *(const f32x4*)(mrow + DM + c0);
;             const f32x4 y = v[j] * rstd * g * (scl + 1.0f) + sh;
;             u32x2 w; w.x = pk2(y.x, y.y); w.y = pk2(y.z, y.w);
;             *(u32x2*)(H + (size_t)r * DM + c0) = w;
;         }
.Lnf_n2_loop:
	s_waitcnt vmcnt(32)
	s_add_u32 s100, s101, s68
	s_cmp_le_u32 s100, s71
	s_cselect_b32 s100, s100, s101
	s_lshr_b32 s8, s100, 8
	s_mul_i32 s8, s8, 57
	s_lshr_b32 s8, s8, 9
	s_mul_i32 s9, s8, 0x900
	s_sub_u32 s9, s100, s9
	s_cmp_lt_u32 s9, 0x100
	s_cselect_b32 s8, 16, s8
	s_mul_i32 s8, s8, 0x6000
	s_add_u32 s0, s24, s8
	s_addc_u32 s1, s25, 0
	global_load_dwordx4 v[88:91], v120, s[0:1] offset:-4096
	global_load_dwordx4 v[92:95], v120, s[0:1] offset:-3072
	global_load_dwordx4 v[96:99], v120, s[0:1] offset:-2048
	global_load_dwordx4 v[100:103], v120, s[0:1] offset:-1024
	global_load_dwordx4 v[104:107], v120, s[0:1]
	global_load_dwordx4 v[108:111], v120, s[0:1] offset:1024
	global_load_dwordx4 v[112:115], v120, s[0:1] offset:2048
	global_load_dwordx4 v[116:119], v120, s[0:1] offset:3072
	v_mul_f32_e32 v32, v1, v1
	v_mul_f32_e32 v33, v3, v3
	v_fmac_f32_e32 v32, v0, v0
	v_fmac_f32_e32 v33, v2, v2
	v_add_f32_e32 v34, v32, v33
	v_mul_f32_e32 v32, v5, v5
	v_mul_f32_e32 v33, v7, v7
	v_fmac_f32_e32 v32, v4, v4
	v_fmac_f32_e32 v33, v6, v6
	v_add_f32_e32 v32, v32, v33
	v_add_f32_e32 v34, v34, v32
	v_mul_f32_e32 v32, v9, v9
	v_mul_f32_e32 v33, v11, v11
	v_fmac_f32_e32 v32, v8, v8
	v_fmac_f32_e32 v33, v10, v10
	v_add_f32_e32 v32, v32, v33
	v_add_f32_e32 v34, v34, v32
	v_mul_f32_e32 v32, v13, v13
	v_mul_f32_e32 v33, v15, v15
	v_fmac_f32_e32 v32, v12, v12
	v_fmac_f32_e32 v33, v14, v14
	v_add_f32_e32 v32, v32, v33
	v_add_f32_e32 v34, v34, v32
	ds_bpermute_b32 v32, v122, v34
	s_waitcnt lgkmcnt(0)
	v_add_f32_e32 v34, v34, v32
	ds_bpermute_b32 v32, v123, v34
	s_waitcnt lgkmcnt(0)
	v_add_f32_e32 v34, v34, v32
	ds_bpermute_b32 v32, v124, v34
	s_waitcnt lgkmcnt(0)
	v_add_f32_e32 v34, v34, v32
	ds_bpermute_b32 v32, v125, v34
	s_waitcnt lgkmcnt(0)
	v_add_f32_e32 v34, v34, v32
	ds_bpermute_b32 v32, v126, v34
	s_waitcnt lgkmcnt(0)
	v_add_f32_e32 v34, v34, v32
	ds_bpermute_b32 v32, v127, v34
	s_waitcnt lgkmcnt(0)
	v_add_f32_e32 v34, v34, v32
	v_fmamk_f32 v34, v34, 0x3a800000, v201
	v_cmp_gt_f32_e32 vcc, 0xf800000, v34
	v_mul_f32_e32 v32, 0x4f800000, v34
	s_nop 0
	v_cndmask_b32_e32 v34, v34, v32, vcc
	v_sqrt_f32_e32 v32, v34
	s_nop 0
	v_add_u32_e32 v35, -1, v32
	v_fma_f32 v36, -v35, v32, v34
	v_cmp_ge_f32_e64 s[42:43], 0, v36
	v_add_u32_e32 v36, 1, v32
	s_nop 0
	v_cndmask_b32_e64 v35, v32, v35, s[42:43]
	v_fma_f32 v32, -v36, v32, v34
	v_cmp_lt_f32_e64 s[42:43], 0, v32
	s_nop 1
	v_cndmask_b32_e64 v32, v35, v36, s[42:43]
	v_mul_f32_e32 v35, 0x37800000, v32
	v_cndmask_b32_e32 v32, v32, v35, vcc
	v_cmp_class_f32_e32 vcc, v34, v202
	s_nop 1
	v_cndmask_b32_e32 v34, v32, v34, vcc
	v_div_scale_f32 v32, s[42:43], v34, v34, 1.0
	v_rcp_f32_e32 v35, v32
	s_nop 0
	v_fma_f32 v36, -v32, v35, 1.0
	v_fmac_f32_e32 v35, v36, v35
	v_div_scale_f32 v36, vcc, 1.0, v34, 1.0
	v_mul_f32_e32 v37, v36, v35
	v_fma_f32 v178, -v32, v37, v36
	v_fmac_f32_e32 v37, v178, v35
	v_fma_f32 v32, -v32, v37, v36
	v_div_fmas_f32 v32, v32, v35, v37
	v_div_fixup_f32 v179, v32, v34, 1.0
	s_lshl_b32 s8, s101, 11
	s_add_u32 s0, s46, s8
	s_addc_u32 s1, s47, 0
	s_add_u32 s0, s0, 0x5500000
	s_addc_u32 s1, s1, 0
	s_waitcnt vmcnt(16)
	v_mul_f32_e32 v193, v0, v179
	v_add_f32_e32 v192, 1.0, v72
	v_mul_f32_e32 v193, v162, v193
	v_fma_f32 v180, v192, v193, v56
	v_mul_f32_e32 v193, v1, v179
	v_add_f32_e32 v192, 1.0, v73
	v_mul_f32_e32 v193, v163, v193
	v_fma_f32 v181, v192, v193, v57
	v_mul_f32_e32 v193, v2, v179
	v_add_f32_e32 v192, 1.0, v74
	v_mul_f32_e32 v193, v164, v193
	v_fma_f32 v182, v192, v193, v58
	v_mul_f32_e32 v193, v3, v179
	v_add_f32_e32 v192, 1.0, v75
	v_mul_f32_e32 v193, v165, v193
	v_fma_f32 v183, v192, v193, v59
	v_cvt_pk_bf16_f32 v184, v180, v181
	v_cvt_pk_bf16_f32 v185, v182, v183
	global_store_dwordx2 v121, v[184:185], s[0:1]
	v_mul_f32_e32 v193, v4, v179
	v_add_f32_e32 v192, 1.0, v76
	v_mul_f32_e32 v193, v166, v193
	v_fma_f32 v180, v192, v193, v60
	v_mul_f32_e32 v193, v5, v179
	v_add_f32_e32 v192, 1.0, v77
	v_mul_f32_e32 v193, v167, v193
	v_fma_f32 v181, v192, v193, v61
	v_mul_f32_e32 v193, v6, v179
	v_add_f32_e32 v192, 1.0, v78
	v_mul_f32_e32 v193, v168, v193
	v_fma_f32 v182, v192, v193, v62
	v_mul_f32_e32 v193, v7, v179
	v_add_f32_e32 v192, 1.0, v79
	v_mul_f32_e32 v193, v169, v193
	v_fma_f32 v183, v192, v193, v63
	v_cvt_pk_bf16_f32 v186, v180, v181
	v_cvt_pk_bf16_f32 v187, v182, v183
	global_store_dwordx2 v121, v[186:187], s[0:1] offset:512
	v_mul_f32_e32 v193, v8, v179
	v_add_f32_e32 v192, 1.0, v80
	v_mul_f32_e32 v193, v170, v193
	v_fma_f32 v180, v192, v193, v64
	v_mul_f32_e32 v193, v9, v179
	v_add_f32_e32 v192, 1.0, v81
	v_mul_f32_e32 v193, v171, v193
	v_fma_f32 v181, v192, v193, v65
	v_mul_f32_e32 v193, v10, v179
	v_add_f32_e32 v192, 1.0, v82
	v_mul_f32_e32 v193, v172, v193
	v_fma_f32 v182, v192, v193, v66
	v_mul_f32_e32 v193, v11, v179
	v_add_f32_e32 v192, 1.0, v83
	v_mul_f32_e32 v193, v173, v193
	v_fma_f32 v183, v192, v193, v67
	v_cvt_pk_bf16_f32 v188, v180, v181
	v_cvt_pk_bf16_f32 v189, v182, v183
	global_store_dwordx2 v121, v[188:189], s[0:1] offset:1024
	v_mul_f32_e32 v193, v12, v179
	v_add_f32_e32 v192, 1.0, v84
	v_mul_f32_e32 v193, v174, v193
	v_fma_f32 v180, v192, v193, v68
	v_mul_f32_e32 v193, v13, v179
	v_add_f32_e32 v192, 1.0, v85
	v_mul_f32_e32 v193, v175, v193
	v_fma_f32 v181, v192, v193, v69
	v_mul_f32_e32 v193, v14, v179
	v_add_f32_e32 v192, 1.0, v86
	v_mul_f32_e32 v193, v176, v193
	v_fma_f32 v182, v192, v193, v70
	v_mul_f32_e32 v193, v15, v179
	v_add_f32_e32 v192, 1.0, v87
	v_mul_f32_e32 v193, v177, v193
	v_fma_f32 v183, v192, v193, v71
	v_cvt_pk_bf16_f32 v190, v180, v181
	v_cvt_pk_bf16_f32 v191, v182, v183
	global_store_dwordx2 v121, v[190:191], s[0:1] offset:1536
	s_mul_i32 s100, s68, 3
	s_add_u32 s100, s100, s101
	s_cmp_le_u32 s100, s71
	s_cselect_b32 s100, s100, s101
	s_lshr_b32 s8, s100, 8
	s_mul_i32 s8, s8, 57
	s_lshr_b32 s8, s8, 9
	s_mul_i32 s9, s8, 0x900
	s_sub_u32 s9, s100, s9
	s_lshl_b32 s0, s8, 11
	s_add_u32 s0, s0, s9
	s_sub_u32 s0, s0, 0x100
	s_lshl_b32 s8, s8, 8
	s_add_u32 s8, s8, s9
	s_cmp_lt_u32 s9, 0x100
	s_cselect_b32 s8, s8, s0
	s_cselect_b32 s0, s36, s44
	s_cselect_b32 s1, s37, s45
	s_lshl_b32 s8, s8, 12
	s_add_u32 s0, s0, s8
	s_addc_u32 s1, s1, 0
	global_load_dwordx4 v[0:3], v120, s[0:1]
	global_load_dwordx4 v[4:7], v120, s[0:1] offset:1024
	global_load_dwordx4 v[8:11], v120, s[0:1] offset:2048
	global_load_dwordx4 v[12:15], v120, s[0:1] offset:3072
	s_add_u32 s101, s101, s68
	s_cmp_gt_u32 s101, s71
	s_cbranch_scc1 .Lnf_n2_exit
; __device__ __forceinline__ unsigned pk2(float lo, float hi) { f32x2_t v = {lo, hi}; bf16x2_t b = __builtin_convertvector(v, bf16x2_t); return __builtin_bit_cast(unsigned, b); }
; __device__ __forceinline__ void phase_norm(const Params& P, int l, int which, bool first) {
;     ...
;     for (int r = gw; r < ROWS; r += NGW) {
;         const int b = r / TT, t = r - b * TT; const int bb = (t < CTX) ? 16 : b;
;         float* xr = xrow_ptr(P, r);
;         const float* src = first ? ((t < CTX) ? P.ctx + ((size_t)b * CTX + t) * DM : P.x + ((size_t)b * SEQ + (t - CTX)) * DM) : xr;
;         f32x4 v[4]; float s2 = 0.f;
; #pragma unroll
;         for (int j = 0; j < 4; ++j) { v[j] = *((const f32x4*)src + lane + 64 * j); s2 += (v[j].x * v[j].x + v[j].y * v[j].y) + (v[j].z * v[j].z + v[j].w * v[j].w); }
;         if (first) {
; #pragma unroll
;             for (int j = 0; j < 4; ++j) *((f32x4*)xr + lane + 64 * j) = v[j];
;         }
;         const float rstd = 1.0f / sqrtf(wave_sum(s2, lane) * (1.0f / DM) + RMS_EPS);
;         const float* mrow = mod + (size_t)bb * MODW;
; #pragma unroll
;         for (int j = 0; j < 4; ++j) {
;             const int c0 = 4 * (lane + 64 * j);
;             const f32x4 g = *(const f32x4*)(gain + c0), sh = *(const f32x4*)(mrow + c0), scl = *(const f32x4*)(mrow + DM + c0);
;             const f32x4 y = v[j] * rstd * g * (scl + 1.0f) + sh;
;             u32x2 w; w.x = pk2(y.x, y.y); w.y = pk2(y.z, y.w);
;             *(u32x2*)(H + (size_t)r * DM + c0) = w;
;         }
	s_waitcnt vmcnt(32)
	s_add_u32 s100, s101, s68
	s_cmp_le_u32 s100, s71
	s_cselect_b32 s100, s100, s101
	s_lshr_b32 s8, s100, 8
	s_mul_i32 s8, s8, 57
	s_lshr_b32 s8, s8, 9
	s_mul_i32 s9, s8, 0x900
	s_sub_u32 s9, s100, s9
	s_cmp_lt_u32 s9, 0x100
	s_cselect_b32 s8, 16, s8
	s_mul_i32 s8, s8, 0x6000
	s_add_u32 s0, s24, s8
	s_addc_u32 s1, s25, 0
	global_load_dwordx4 v[130:133], v120, s[0:1] offset:-4096
	global_load_dwordx4 v[134:137], v120, s[0:1] offset:-3072
	global_load_dwordx4 v[138:141], v120, s[0:1] offset:-2048
	global_load_dwordx4 v[142:145], v120, s[0:1] offset:-1024
	global_load_dwordx4 v[146:149], v120, s[0:1]
	global_load_dwordx4 v[150:153], v120, s[0:1] offset:1024
	global_load_dwordx4 v[154:157], v120, s[0:1] offset:2048
	global_load_dwordx4 v[158:161], v120, s[0:1] offset:3072
	v_mul_f32_e32 v32, v17, v17
	v_mul_f32_e32 v33, v19, v19
	v_fmac_f32_e32 v32, v16, v16
	v_fmac_f32_e32 v33, v18, v18
	v_add_f32_e32 v34, v32, v33
	v_mul_f32_e32 v32, v21, v21
	v_mul_f32_e32 v33, v23, v23
	v_fmac_f32_e32 v32, v20, v20
	v_fmac_f32_e32 v33, v22, v22
	v_add_f32_e32 v32, v32, v33
	v_add_f32_e32 v34, v34, v32
	v_mul_f32_e32 v32, v25, v25
	v_mul_f32_e32 v33, v27, v27
	v_fmac_f32_e32 v32, v24, v24
	v_fmac_f32_e32 v33, v26, v26
	v_add_f32_e32 v32, v32, v33
	v_add_f32_e32 v34, v34, v32
	v_mul_f32_e32 v32, v29, v29
	v_mul_f32_e32 v33, v31, v31
	v_fmac_f32_e32 v32, v28, v28
	v_fmac_f32_e32 v33, v30, v30
	v_add_f32_e32 v32, v32, v33
	v_add_f32_e32 v34, v34, v32
	ds_bpermute_b32 v32, v122, v34
	s_waitcnt lgkmcnt(0)
	v_add_f32_e32 v34, v34, v32
	ds_bpermute_b32 v32, v123, v34
	s_waitcnt lgkmcnt(0)
	v_add_f32_e32 v34, v34, v32
	ds_bpermute_b32 v32, v124, v34
	s_waitcnt lgkmcnt(0)
	v_add_f32_e32 v34, v34, v32
	ds_bpermute_b32 v32, v125, v34
	s_waitcnt lgkmcnt(0)
	v_add_f32_e32 v34, v34, v32
	ds_bpermute_b32 v32, v126, v34
	s_waitcnt lgkmcnt(0)
	v_add_f32_e32 v34, v34, v32
	ds_bpermute_b32 v32, v127, v34
	s_waitcnt lgkmcnt(0)
	v_add_f32_e32 v34, v34, v32
	v_fmamk_f32 v34, v34, 0x3a800000, v201
	v_cmp_gt_f32_e32 vcc, 0xf800000, v34
	v_mul_f32_e32 v32, 0x4f800000, v34
	s_nop 0
	v_cndmask_b32_e32 v34, v34, v32, vcc
	v_sqrt_f32_e32 v32, v34
	s_nop 0
	v_add_u32_e32 v35, -1, v32
	v_fma_f32 v36, -v35, v32, v34
	v_cmp_ge_f32_e64 s[42:43], 0, v36
	v_add_u32_e32 v36, 1, v32
	s_nop 0
	v_cndmask_b32_e64 v35, v32, v35, s[42:43]
	v_fma_f32 v32, -v36, v32, v34
	v_cmp_lt_f32_e64 s[42:43], 0, v32
	s_nop 1
	v_cndmask_b32_e64 v32, v35, v36, s[42:43]
	v_mul_f32_e32 v35, 0x37800000, v32
	v_cndmask_b32_e32 v32, v32, v35, vcc
	v_cmp_class_f32_e32 vcc, v34, v202
	s_nop 1
	v_cndmask_b32_e32 v34, v32, v34, vcc
	v_div_scale_f32 v32, s[42:43], v34, v34, 1.0
	v_rcp_f32_e32 v35, v32
	s_nop 0
	v_fma_f32 v36, -v32, v35, 1.0
	v_fmac_f32_e32 v35, v36, v35
	v_div_scale_f32 v36, vcc, 1.0, v34, 1.0
	v_mul_f32_e32 v37, v36, v35
	v_fma_f32 v178, -v32, v37, v36
	v_fmac_f32_e32 v37, v178, v35
	v_fma_f32 v32, -v32, v37, v36
	v_div_fmas_f32 v32, v32, v35, v37
	v_div_fixup_f32 v179, v32, v34, 1.0
	s_lshl_b32 s8, s101, 11
	s_add_u32 s0, s46, s8
	s_addc_u32 s1, s47, 0
	s_add_u32 s0, s0, 0x5500000
	s_addc_u32 s1, s1, 0
	s_waitcnt vmcnt(16)
	v_mul_f32_e32 v193, v16, v179
	v_add_f32_e32 v192, 1.0, v104
	v_mul_f32_e32 v193, v162, v193
	v_fma_f32 v180, v192, v193, v88
	v_mul_f32_e32 v193, v17, v179
	v_add_f32_e32 v192, 1.0, v105
	v_mul_f32_e32 v193, v163, v193
	v_fma_f32 v181, v192, v193, v89
	v_mul_f32_e32 v193, v18, v179
	v_add_f32_e32 v192, 1.0, v106
	v_mul_f32_e32 v193, v164, v193
	v_fma_f32 v182, v192, v193, v90
	v_mul_f32_e32 v193, v19, v179
	v_add_f32_e32 v192, 1.0, v107
	v_mul_f32_e32 v193, v165, v193
	v_fma_f32 v183, v192, v193, v91
	v_cvt_pk_bf16_f32 v184, v180, v181
	v_cvt_pk_bf16_f32 v185, v182, v183
	global_store_dwordx2 v121, v[184:185], s[0:1]
	v_mul_f32_e32 v193, v20, v179
	v_add_f32_e32 v192, 1.0, v108
	v_mul_f32_e32 v193, v166, v193
	v_fma_f32 v180, v192, v193, v92
	v_mul_f32_e32 v193, v21, v179
	v_add_f32_e32 v192, 1.0, v109
	v_mul_f32_e32 v193, v167, v193
	v_fma_f32 v181, v192, v193, v93
	v_mul_f32_e32 v193, v22, v179
	v_add_f32_e32 v192, 1.0, v110
	v_mul_f32_e32 v193, v168, v193
	v_fma_f32 v182, v192, v193, v94
	v_mul_f32_e32 v193, v23, v179
	v_add_f32_e32 v192, 1.0, v111
	v_mul_f32_e32 v193, v169, v193
	v_fma_f32 v183, v192, v193, v95
	v_cvt_pk_bf16_f32 v186, v180, v181
	v_cvt_pk_bf16_f32 v187, v182, v183
	global_store_dwordx2 v121, v[186:187], s[0:1] offset:512
	v_mul_f32_e32 v193, v24, v179
	v_add_f32_e32 v192, 1.0, v112
	v_mul_f32_e32 v193, v170, v193
	v_fma_f32 v180, v192, v193, v96
	v_mul_f32_e32 v193, v25, v179
	v_add_f32_e32 v192, 1.0, v113
	v_mul_f32_e32 v193, v171, v193
	v_fma_f32 v181, v192, v193, v97
	v_mul_f32_e32 v193, v26, v179
	v_add_f32_e32 v192, 1.0, v114
	v_mul_f32_e32 v193, v172, v193
	v_fma_f32 v182, v192, v193, v98
	v_mul_f32_e32 v193, v27, v179
	v_add_f32_e32 v192, 1.0, v115
	v_mul_f32_e32 v193, v173, v193
	v_fma_f32 v183, v192, v193, v99
	v_cvt_pk_bf16_f32 v188, v180, v181
	v_cvt_pk_bf16_f32 v189, v182, v183
	global_store_dwordx2 v121, v[188:189], s[0:1] offset:1024
	v_mul_f32_e32 v193, v28, v179
	v_add_f32_e32 v192, 1.0, v116
	v_mul_f32_e32 v193, v174, v193
	v_fma_f32 v180, v192, v193, v100
	v_mul_f32_e32 v193, v29, v179
	v_add_f32_e32 v192, 1.0, v117
	v_mul_f32_e32 v193, v175, v193
	v_fma_f32 v181, v192, v193, v101
	v_mul_f32_e32 v193, v30, v179
	v_add_f32_e32 v192, 1.0, v118
	v_mul_f32_e32 v193, v176, v193
	v_fma_f32 v182, v192, v193, v102
	v_mul_f32_e32 v193, v31, v179
	v_add_f32_e32 v192, 1.0, v119
	v_mul_f32_e32 v193, v177, v193
	v_fma_f32 v183, v192, v193, v103
	v_cvt_pk_bf16_f32 v190, v180, v181
	v_cvt_pk_bf16_f32 v191, v182, v183
	global_store_dwordx2 v121, v[190:191], s[0:1] offset:1536
	s_mul_i32 s100, s68, 3
	s_add_u32 s100, s100, s101
	s_cmp_le_u32 s100, s71
	s_cselect_b32 s100, s100, s101
	s_lshr_b32 s8, s100, 8
	s_mul_i32 s8, s8, 57
	s_lshr_b32 s8, s8, 9
	s_mul_i32 s9, s8, 0x900
	s_sub_u32 s9, s100, s9
	s_lshl_b32 s0, s8, 11
	s_add_u32 s0, s0, s9
	s_sub_u32 s0, s0, 0x100
	s_lshl_b32 s8, s8, 8
	s_add_u32 s8, s8, s9
	s_cmp_lt_u32 s9, 0x100
	s_cselect_b32 s8, s8, s0
	s_cselect_b32 s0, s36, s44
	s_cselect_b32 s1, s37, s45
	s_lshl_b32 s8, s8, 12
	s_add_u32 s0, s0, s8
	s_addc_u32 s1, s1, 0
	global_load_dwordx4 v[16:19], v120, s[0:1]
	global_load_dwordx4 v[20:23], v120, s[0:1] offset:1024
	global_load_dwordx4 v[24:27], v120, s[0:1] offset:2048
	global_load_dwordx4 v[28:31], v120, s[0:1] offset:3072
	s_add_u32 s101, s101, s68
	s_cmp_gt_u32 s101, s71
	s_cbranch_scc1 .Lnf_n2_exit
; __device__ __forceinline__ unsigned pk2(float lo, float hi) { f32x2_t v = {lo, hi}; bf16x2_t b = __builtin_convertvector(v, bf16x2_t); return __builtin_bit_cast(unsigned, b); }
; __device__ __forceinline__ void phase_norm(const Params& P, int l, int which, bool first) {
;     ...
;     for (int r = gw; r < ROWS; r += NGW) {
;         const int b = r / TT, t = r - b * TT; const int bb = (t < CTX) ? 16 : b;
;         float* xr = xrow_ptr(P, r);
;         const float* src = first ? ((t < CTX) ? P.ctx + ((size_t)b * CTX + t) * DM : P.x + ((size_t)b * SEQ + (t - CTX)) * DM) : xr;
;         f32x4 v[4]; float s2 = 0.f;
; #pragma unroll
;         for (int j = 0; j < 4; ++j) { v[j] = *((const f32x4*)src + lane + 64 * j); s2 += (v[j].x * v[j].x + v[j].y * v[j].y) + (v[j].z * v[j].z + v[j].w * v[j].w); }
;         if (first) {
; #pragma unroll
;             for (int j = 0; j < 4; ++j) *((f32x4*)xr + lane + 64 * j) = v[j];
;         }
;         const float rstd = 1.0f / sqrtf(wave_sum(s2, lane) * (1.0f / DM) + RMS_EPS);
;         const float* mrow = mod + (size_t)bb * MODW;
; #pragma unroll
;         for (int j = 0; j < 4; ++j) {
;             const int c0 = 4 * (lane + 64 * j);
;             const f32x4 g = *(const f32x4*)(gain + c0), sh = *(const f32x4*)(mrow + c0), scl = *(const f32x4*)(mrow + DM + c0);
;             const f32x4 y = v[j] * rstd * g * (scl + 1.0f) + sh;
;             u32x2 w; w.x = pk2(y.x, y.y); w.y = pk2(y.z, y.w);
;             *(u32x2*)(H + (size_t)r * DM + c0) = w;
;         }
	s_waitcnt vmcnt(32)
	s_add_u32 s100, s101, s68
	s_cmp_le_u32 s100, s71
	s_cselect_b32 s100, s100, s101
	s_lshr_b32 s8, s100, 8
	s_mul_i32 s8, s8, 57
	s_lshr_b32 s8, s8, 9
	s_mul_i32 s9, s8, 0x900
	s_sub_u32 s9, s100, s9
	s_cmp_lt_u32 s9, 0x100
	s_cselect_b32 s8, 16, s8
	s_mul_i32 s8, s8, 0x6000
	s_add_u32 s0, s24, s8
	s_addc_u32 s1, s25, 0
	global_load_dwordx4 v[56:59], v120, s[0:1] offset:-4096
	global_load_dwordx4 v[60:63], v120, s[0:1] offset:-3072
	global_load_dwordx4 v[64:67], v120, s[0:1] offset:-2048
	global_load_dwordx4 v[68:71], v120, s[0:1] offset:-1024
	global_load_dwordx4 v[72:75], v120, s[0:1]
	global_load_dwordx4 v[76:79], v120, s[0:1] offset:1024
	global_load_dwordx4 v[80:83], v120, s[0:1] offset:2048
	global_load_dwordx4 v[84:87], v120, s[0:1] offset:3072
	v_mul_f32_e32 v32, v41, v41
	v_mul_f32_e32 v33, v43, v43
	v_fmac_f32_e32 v32, v40, v40
	v_fmac_f32_e32 v33, v42, v42
	v_add_f32_e32 v34, v32, v33
	v_mul_f32_e32 v32, v45, v45
	v_mul_f32_e32 v33, v47, v47
	v_fmac_f32_e32 v32, v44, v44
	v_fmac_f32_e32 v33, v46, v46
	v_add_f32_e32 v32, v32, v33
	v_add_f32_e32 v34, v34, v32
	v_mul_f32_e32 v32, v49, v49
	v_mul_f32_e32 v33, v51, v51
	v_fmac_f32_e32 v32, v48, v48
	v_fmac_f32_e32 v33, v50, v50
	v_add_f32_e32 v32, v32, v33
	v_add_f32_e32 v34, v34, v32
	v_mul_f32_e32 v32, v53, v53
	v_mul_f32_e32 v33, v55, v55
	v_fmac_f32_e32 v32, v52, v52
	v_fmac_f32_e32 v33, v54, v54
	v_add_f32_e32 v32, v32, v33
	v_add_f32_e32 v34, v34, v32
	ds_bpermute_b32 v32, v122, v34
	s_waitcnt lgkmcnt(0)
	v_add_f32_e32 v34, v34, v32
	ds_bpermute_b32 v32, v123, v34
	s_waitcnt lgkmcnt(0)
	v_add_f32_e32 v34, v34, v32
	ds_bpermute_b32 v32, v124, v34
	s_waitcnt lgkmcnt(0)
	v_add_f32_e32 v34, v34, v32
	ds_bpermute_b32 v32, v125, v34
	s_waitcnt lgkmcnt(0)
	v_add_f32_e32 v34, v34, v32
	ds_bpermute_b32 v32, v126, v34
	s_waitcnt lgkmcnt(0)
	v_add_f32_e32 v34, v34, v32
	ds_bpermute_b32 v32, v127, v34
	s_waitcnt lgkmcnt(0)
	v_add_f32_e32 v34, v34, v32
	v_fmamk_f32 v34, v34, 0x3a800000, v201
	v_cmp_gt_f32_e32 vcc, 0xf800000, v34
	v_mul_f32_e32 v32, 0x4f800000, v34
	s_nop 0
	v_cndmask_b32_e32 v34, v34, v32, vcc
	v_sqrt_f32_e32 v32, v34
	s_nop 0
	v_add_u32_e32 v35, -1, v32
	v_fma_f32 v36, -v35, v32, v34
	v_cmp_ge_f32_e64 s[42:43], 0, v36
	v_add_u32_e32 v36, 1, v32
	s_nop 0
	v_cndmask_b32_e64 v35, v32, v35, s[42:43]
	v_fma_f32 v32, -v36, v32, v34
	v_cmp_lt_f32_e64 s[42:43], 0, v32
	s_nop 1
	v_cndmask_b32_e64 v32, v35, v36, s[42:43]
	v_mul_f32_e32 v35, 0x37800000, v32
	v_cndmask_b32_e32 v32, v32, v35, vcc
	v_cmp_class_f32_e32 vcc, v34, v202
	s_nop 1
	v_cndmask_b32_e32 v34, v32, v34, vcc
	v_div_scale_f32 v32, s[42:43], v34, v34, 1.0
	v_rcp_f32_e32 v35, v32
	s_nop 0
	v_fma_f32 v36, -v32, v35, 1.0
	v_fmac_f32_e32 v35, v36, v35
	v_div_scale_f32 v36, vcc, 1.0, v34, 1.0
	v_mul_f32_e32 v37, v36, v35
	v_fma_f32 v178, -v32, v37, v36
	v_fmac_f32_e32 v37, v178, v35
	v_fma_f32 v32, -v32, v37, v36
	v_div_fmas_f32 v32, v32, v35, v37
	v_div_fixup_f32 v179, v32, v34, 1.0
	s_lshl_b32 s8, s101, 11
	s_add_u32 s0, s46, s8
	s_addc_u32 s1, s47, 0
	s_add_u32 s0, s0, 0x5500000
	s_addc_u32 s1, s1, 0
	s_waitcnt vmcnt(16)
	v_mul_f32_e32 v193, v40, v179
	v_add_f32_e32 v192, 1.0, v146
	v_mul_f32_e32 v193, v162, v193
	v_fma_f32 v180, v192, v193, v130
	v_mul_f32_e32 v193, v41, v179
	v_add_f32_e32 v192, 1.0, v147
	v_mul_f32_e32 v193, v163, v193
	v_fma_f32 v181, v192, v193, v131
	v_mul_f32_e32 v193, v42, v179
	v_add_f32_e32 v192, 1.0, v148
	v_mul_f32_e32 v193, v164, v193
	v_fma_f32 v182, v192, v193, v132
	v_mul_f32_e32 v193, v43, v179
	v_add_f32_e32 v192, 1.0, v149
	v_mul_f32_e32 v193, v165, v193
	v_fma_f32 v183, v192, v193, v133
	v_cvt_pk_bf16_f32 v184, v180, v181
	v_cvt_pk_bf16_f32 v185, v182, v183
	global_store_dwordx2 v121, v[184:185], s[0:1]
	v_mul_f32_e32 v193, v44, v179
	v_add_f32_e32 v192, 1.0, v150
	v_mul_f32_e32 v193, v166, v193
	v_fma_f32 v180, v192, v193, v134
	v_mul_f32_e32 v193, v45, v179
	v_add_f32_e32 v192, 1.0, v151
	v_mul_f32_e32 v193, v167, v193
	v_fma_f32 v181, v192, v193, v135
	v_mul_f32_e32 v193, v46, v179
	v_add_f32_e32 v192, 1.0, v152
	v_mul_f32_e32 v193, v168, v193
	v_fma_f32 v182, v192, v193, v136
	v_mul_f32_e32 v193, v47, v179
	v_add_f32_e32 v192, 1.0, v153
	v_mul_f32_e32 v193, v169, v193
	v_fma_f32 v183, v192, v193, v137
	v_cvt_pk_bf16_f32 v186, v180, v181
	v_cvt_pk_bf16_f32 v187, v182, v183
	global_store_dwordx2 v121, v[186:187], s[0:1] offset:512
	v_mul_f32_e32 v193, v48, v179
	v_add_f32_e32 v192, 1.0, v154
	v_mul_f32_e32 v193, v170, v193
	v_fma_f32 v180, v192, v193, v138
	v_mul_f32_e32 v193, v49, v179
	v_add_f32_e32 v192, 1.0, v155
	v_mul_f32_e32 v193, v171, v193
	v_fma_f32 v181, v192, v193, v139
	v_mul_f32_e32 v193, v50, v179
	v_add_f32_e32 v192, 1.0, v156
	v_mul_f32_e32 v193, v172, v193
	v_fma_f32 v182, v192, v193, v140
	v_mul_f32_e32 v193, v51, v179
	v_add_f32_e32 v192, 1.0, v157
	v_mul_f32_e32 v193, v173, v193
	v_fma_f32 v183, v192, v193, v141
	v_cvt_pk_bf16_f32 v188, v180, v181
	v_cvt_pk_bf16_f32 v189, v182, v183
	global_store_dwordx2 v121, v[188:189], s[0:1] offset:1024
	v_mul_f32_e32 v193, v52, v179
	v_add_f32_e32 v192, 1.0, v158
	v_mul_f32_e32 v193, v174, v193
	v_fma_f32 v180, v192, v193, v142
	v_mul_f32_e32 v193, v53, v179
	v_add_f32_e32 v192, 1.0, v159
	v_mul_f32_e32 v193, v175, v193
	v_fma_f32 v181, v192, v193, v143
	v_mul_f32_e32 v193, v54, v179
	v_add_f32_e32 v192, 1.0, v160
	v_mul_f32_e32 v193, v176, v193
	v_fma_f32 v182, v192, v193, v144
	v_mul_f32_e32 v193, v55, v179
	v_add_f32_e32 v192, 1.0, v161
	v_mul_f32_e32 v193, v177, v193
	v_fma_f32 v183, v192, v193, v145
	v_cvt_pk_bf16_f32 v190, v180, v181
	v_cvt_pk_bf16_f32 v191, v182, v183
	global_store_dwordx2 v121, v[190:191], s[0:1] offset:1536
	s_mul_i32 s100, s68, 3
	s_add_u32 s100, s100, s101
	s_cmp_le_u32 s100, s71
	s_cselect_b32 s100, s100, s101
	s_lshr_b32 s8, s100, 8
	s_mul_i32 s8, s8, 57
	s_lshr_b32 s8, s8, 9
	s_mul_i32 s9, s8, 0x900
	s_sub_u32 s9, s100, s9
	s_lshl_b32 s0, s8, 11
	s_add_u32 s0, s0, s9
	s_sub_u32 s0, s0, 0x100
	s_lshl_b32 s8, s8, 8
	s_add_u32 s8, s8, s9
	s_cmp_lt_u32 s9, 0x100
	s_cselect_b32 s8, s8, s0
	s_cselect_b32 s0, s36, s44
	s_cselect_b32 s1, s37, s45
	s_lshl_b32 s8, s8, 12
	s_add_u32 s0, s0, s8
	s_addc_u32 s1, s1, 0
	global_load_dwordx4 v[40:43], v120, s[0:1]
	global_load_dwordx4 v[44:47], v120, s[0:1] offset:1024
	global_load_dwordx4 v[48:51], v120, s[0:1] offset:2048
	global_load_dwordx4 v[52:55], v120, s[0:1] offset:3072
	s_add_u32 s101, s101, s68
	s_cmp_gt_u32 s101, s71
	s_cbranch_scc1 .Lnf_n2_exit
	s_branch .Lnf_n2_loop
; __device__ __forceinline__ void xcd_barrier(const XcdBarrier& b) {
;     asm volatile("s_waitcnt vmcnt(0)" ::: "memory");
;     __syncthreads();
;     if (threadIdx.x == 0) {
;         unsigned* bar = b.bar;
;         __builtin_amdgcn_s_waitcnt(0);
;         unsigned nloc = b.st[0], nx = b.st[1];
;         if (nloc == 0u) { xcd_barrier_complete(bar, b.x, nloc, nx); b.st[0] = nloc; b.st[1] = nx; }
.Lnf_n2_exit:
	s_waitcnt vmcnt(0)
.LBB0_940:
	s_mov_b32 s7, 0xf800000
	s_or_b64 exec, exec, s[10:11]
	s_waitcnt vmcnt(0)
	s_barrier
	s_mov_b64 s[10:11], exec
	v_readlane_b32 s0, v253, 0
	v_readlane_b32 s1, v253, 1
	s_and_b64 s[0:1], s[10:11], s[0:1]
	s_mov_b64 exec, s[0:1]
	s_cbranch_execz .LBB0_992
	v_readlane_b32 s0, v254, 24
	s_waitcnt vmcnt(0) expcnt(0) lgkmcnt(0)
	s_nop 0
	v_mov_b32_e32 v0, s0
	ds_read_b32 v2, v0
	v_readlane_b32 s0, v254, 25
	s_waitcnt lgkmcnt(0)
	v_cmp_ne_u32_e32 vcc, 0, v2
	v_mov_b32_e32 v0, s0
	ds_read_b32 v0, v0
	s_cbranch_vccnz .LBB0_956
	s_mov_b32 s0, 1
	s_branch .LBB0_944
